# v9 with an explicit lgkmcnt bound before the second batch of SSD state-update LDS reads (robustness; no timing intent)
# speedup vs baseline: 1.0045x; 1.0045x over previous
; #define LAS __attribute__((address_space(3)))
; __device__ __forceinline__ unsigned pkbf(float lo, float hi) { f32x2v v = {lo, hi}; bf16x2v b = __builtin_convertvector(v, bf16x2v); return __builtin_bit_cast(unsigned, b); }
; DI float bf_lo(unsigned w) { return __uint_as_float(w << 16); }
; DI float bf_hi(unsigned w) { return __uint_as_float(w & 0xffff0000u); }
; DI float silu_f(float x) { return x * __builtin_amdgcn_rcpf(1.0f + __builtin_amdgcn_exp2f(-1.4426950408889634f * x)); }
; #define MFMA16(a, b, c) __builtin_amdgcn_mfma_f32_16x16x32_bf16((a), (b), (c), 0, 0, 0)
; DI void ssd_unit(LAS unsigned char* lds, const bf16* XBC, const float* DT, const bf16* PROJ, bf16* YG, int rb, int NC, int h, float A, float Dsk, const float* h0, float* hout, int tid) {
;     ...
;             const float x0 = bf_lo(gx[pt].x), x1 = bf_hi(gx[pt].x), x2 = bf_lo(gx[pt].y), x3 = bf_hi(gx[pt].y);
;             const float z0 = bf_lo(gz[pt].x), z1 = bf_hi(gz[pt].x), z2 = bf_lo(gz[pt].y), z3 = bf_hi(gz[pt].y);
;             u32x2 w; w.x = pkbf((y[0] + Dsk * x0) * silu_f(z0), (y[1] + Dsk * x1) * silu_f(z1)); w.y = pkbf((y[2] + Dsk * x2) * silu_f(z2), (y[3] + Dsk * x3) * silu_f(z3));
;             *(u32x2*)(YG + (size_t)(row0 + i) * 2048 + h * 64 + 16 * pb + 4 * quad) = w;
;         }
;         const float et = __expf(atot);
; #pragma unroll
;         for (int t = 0; t < 4; ++t) hacc[t] *= et;
; #pragma unroll
;         for (int s = 0; s < 2; ++s) {
;             const bf16x8 xf = tr_frag(T + XW, RSX, 32 * s, 16 * pbk, lane);
; #pragma unroll
;             for (int t = 0; t < 4; ++t) hacc[t] = MFMA16(tr_frag(T + BS, RSC, 32 * s, 16 * (nb0 + t), lane), xf, hacc[t]);
;         }
; #pragma unroll
;         for (int t = 0; t < 4; ++t) { u32x2 w; w.x = pkbf(hacc[t][0], hacc[t][1]); w.y = pkbf(hacc[t][2], hacc[t][3]);
;             *(LAS u32x2*)(Hn + (16 * pbk + l15) * RSC + (16 * (nb0 + t) + 4 * quad) * 2) = w; }
.LBB0_1143:
	s_or_b64 exec, exec, s[0:1]
	v_add_u32_e32 v236, s62, v154
	v_add_u32_e32 v237, v97, v168
	v_add3_u32 v236, v236, v153, v167
	v_add_u32_e32 v238, v237, v93
	ds_read_b64_tr_b16 v[188:189], v236 offset:44032
	ds_read_b64_tr_b16 v[190:191], v236 offset:44608
	ds_read_b64_tr_b16 v[192:193], v238 offset:17408
	ds_read_b64_tr_b16 v[194:195], v238 offset:18496
	v_add_u32_e32 v238, v237, v138
	ds_read_b64_tr_b16 v[196:197], v238 offset:17408
	ds_read_b64_tr_b16 v[198:199], v238 offset:18496
	v_add_u32_e32 v238, v237, v139
	ds_read_b64_tr_b16 v[200:201], v238 offset:17408
	ds_read_b64_tr_b16 v[202:203], v238 offset:18496
	v_add_u32_e32 v238, v237, v140
	ds_read_b64_tr_b16 v[204:205], v238 offset:17408
	ds_read_b64_tr_b16 v[206:207], v238 offset:18496
	v_lshlrev_b32_e32 v54, 16, v126
	v_mul_f32_e32 v1, 0xbfb8aa3b, v54
	v_exp_f32_e32 v1, v1
	v_and_b32_e32 v55, 0xffff0000, v126
	v_lshlrev_b32_e32 v52, 16, v128
	v_and_b32_e32 v53, 0xffff0000, v128
	v_add_f32_e32 v1, 1.0, v1
	v_rcp_f32_e32 v56, v1
	v_mul_f32_e32 v1, 0xbfb8aa3b, v55
	v_exp_f32_e32 v1, v1
	v_pk_fma_f32 v[48:49], v[102:103], v[52:53], v[48:49]
	v_mov_b32_e32 v99, v3
	s_mulk_i32 s27, 0x4400
	v_add_f32_e32 v1, 1.0, v1
	v_rcp_f32_e32 v57, v1
	s_mov_b64 s[0:1], 0xf8000
	v_add_u32_e32 v106, 64, v106
	v_lshl_add_u64 v[112:113], v[112:113], 0, s[68:69]
	v_pk_mul_f32 v[52:53], v[56:57], v[54:55]
	v_lshlrev_b32_e32 v54, 16, v127
	v_mul_f32_e32 v1, 0xbfb8aa3b, v54
	v_exp_f32_e32 v1, v1
	v_and_b32_e32 v55, 0xffff0000, v127
	v_pk_mul_f32 v[48:49], v[52:53], v[48:49]
	v_lshlrev_b32_e32 v52, 16, v129
	v_add_f32_e32 v1, 1.0, v1
	v_rcp_f32_e32 v56, v1
	v_mul_f32_e32 v1, 0xbfb8aa3b, v55
	v_exp_f32_e32 v1, v1
	v_and_b32_e32 v53, 0xffff0000, v129
	v_pk_fma_f32 v[50:51], v[102:103], v[52:53], v[50:51]
	v_cvt_pk_bf16_f32 v48, v48, v49
	v_add_f32_e32 v1, 1.0, v1
	v_rcp_f32_e32 v57, v1
	v_mov_b32_e32 v1, 0x3fb8aa3b
	v_mul_f32_e32 v1, s11, v1
	v_lshl_add_u64 v[108:109], v[108:109], 0, s[30:31]
	v_pk_mul_f32 v[52:53], v[56:57], v[54:55]
	v_add_u32_e32 v239, v97, v169
	v_pk_mul_f32 v[50:51], v[52:53], v[50:51]
	v_add_u32_e32 v238, v239, v93
	v_cvt_pk_bf16_f32 v49, v50, v51
	v_lshl_add_u64 v[50:51], v[134:135], 0, v[98:99]
	global_store_dwordx2 v[50:51], v[48:49], off
	v_exp_f32_e32 v48, v1
	s_waitcnt lgkmcnt(5)
	ds_read_b64_tr_b16 v[208:209], v236 offset:48640
	ds_read_b64_tr_b16 v[210:211], v236 offset:49216
	ds_read_b64_tr_b16 v[212:213], v238 offset:17408
	ds_read_b64_tr_b16 v[214:215], v238 offset:18496
	v_add_u32_e32 v238, v239, v138
	ds_read_b64_tr_b16 v[216:217], v238 offset:17408
	ds_read_b64_tr_b16 v[218:219], v238 offset:18496
	v_add_u32_e32 v238, v239, v139
	ds_read_b64_tr_b16 v[220:221], v238 offset:17408
	ds_read_b64_tr_b16 v[222:223], v238 offset:18496
	v_add_u32_e32 v238, v239, v140
	ds_read_b64_tr_b16 v[232:233], v238 offset:17408
	ds_read_b64_tr_b16 v[234:235], v238 offset:18496
	v_lshl_add_u64 v[110:111], v[110:111], 0, s[30:31]
	v_pk_mul_f32 v[10:11], v[10:11], v[48:49] op_sel_hi:[1,0]
	v_pk_mul_f32 v[8:9], v[8:9], v[48:49] op_sel_hi:[1,0]
	v_pk_mul_f32 v[14:15], v[14:15], v[48:49] op_sel_hi:[1,0]
	v_pk_mul_f32 v[12:13], v[12:13], v[48:49] op_sel_hi:[1,0]
	v_pk_mul_f32 v[18:19], v[18:19], v[48:49] op_sel_hi:[1,0]
	v_pk_mul_f32 v[16:17], v[16:17], v[48:49] op_sel_hi:[1,0]
	v_pk_mul_f32 v[34:35], v[34:35], v[48:49] op_sel_hi:[1,0]
	v_pk_mul_f32 v[32:33], v[32:33], v[48:49] op_sel_hi:[1,0]
	s_waitcnt lgkmcnt(15)
	v_mfma_f32_16x16x32_bf16 v[8:11], v[192:195], v[188:191], v[8:11]
	s_waitcnt lgkmcnt(14)
	v_mfma_f32_16x16x32_bf16 v[12:15], v[196:199], v[188:191], v[12:15]
	s_waitcnt lgkmcnt(12)
	v_mfma_f32_16x16x32_bf16 v[16:19], v[200:203], v[188:191], v[16:19]
	s_waitcnt lgkmcnt(10)
	v_mfma_f32_16x16x32_bf16 v[32:35], v[204:207], v[188:191], v[32:35]
	s_waitcnt lgkmcnt(6)
	v_mfma_f32_16x16x32_bf16 v[8:11], v[212:215], v[208:211], v[8:11]
	s_waitcnt lgkmcnt(4)
	v_mfma_f32_16x16x32_bf16 v[12:15], v[216:219], v[208:211], v[12:15]
	s_waitcnt lgkmcnt(2)
	v_mfma_f32_16x16x32_bf16 v[16:19], v[220:223], v[208:211], v[16:19]
	s_waitcnt lgkmcnt(0)
	v_mfma_f32_16x16x32_bf16 v[32:35], v[232:235], v[208:211], v[32:35]
	v_lshl_add_u64 v[116:117], v[116:117], 0, s[0:1]
	v_lshl_add_u64 v[104:105], v[104:105], 0, s[30:31]
	s_add_i32 s100, s63, 2
	s_cmp_lt_u32 s100, s9
	s_cbranch_scc1 .Lssd_wait_g8
	s_waitcnt vmcnt(2)
	s_branch .Lssd_wait_gdone
